# GEMM K-loops: even half-step A-fragment ds_reads issued right after the barrier, ahead of the W loads and LDS-DMA issue
# baseline (speedup 1.0000x reference)
.Lg1_loop:
	s_waitcnt vmcnt(12)
	s_barrier
	v_add_u32_e32 v244, s28, v242
	v_add_u32_e32 v245, s28, v243
	ds_read_b128 v[198:201], v244 offset:0
	ds_read_b128 v[202:205], v244 offset:2048
	ds_read_b128 v[210:213], v244 offset:4096
	ds_read_b128 v[214:217], v244 offset:6144
	ds_read_b128 v[218:221], v244 offset:8192
	ds_read_b128 v[222:225], v244 offset:10240
	ds_read_b128 v[226:229], v244 offset:12288
	ds_read_b128 v[230:233], v244 offset:14336
	global_load_dwordx4 v[176:179], v238, s[56:57]
	global_load_dwordx4 v[182:185], v239, s[56:57]
	global_load_dwordx4 v[186:189], v240, s[56:57]
	global_load_dwordx4 v[194:197], v241, s[56:57]
	s_cmp_eq_u32 s25, 31
	s_cbranch_scc1 .Lg1_sww0
	s_add_u32 s56, s56, 1024
	s_addc_u32 s57, s57, 0
	s_branch .Lg1_swdw0

.Lg1_nda1:
.Lg1_sada1:
	s_waitcnt lgkmcnt(4)
	v_mfma_f32_16x16x32_bf16 v[0:3], v[128:131], v[198:201], v[0:3]
	v_mfma_f32_16x16x32_bf16 v[32:35], v[132:135], v[198:201], v[32:35]
	v_mfma_f32_16x16x32_bf16 v[64:67], v[136:139], v[198:201], v[64:67]
	v_mfma_f32_16x16x32_bf16 v[96:99], v[140:143], v[198:201], v[96:99]
	v_mfma_f32_16x16x32_bf16 v[4:7], v[128:131], v[202:205], v[4:7]
	v_mfma_f32_16x16x32_bf16 v[36:39], v[132:135], v[202:205], v[36:39]
	v_mfma_f32_16x16x32_bf16 v[68:71], v[136:139], v[202:205], v[68:71]
	v_mfma_f32_16x16x32_bf16 v[100:103], v[140:143], v[202:205], v[100:103]
	v_mfma_f32_16x16x32_bf16 v[8:11], v[128:131], v[210:213], v[8:11]
	v_mfma_f32_16x16x32_bf16 v[40:43], v[132:135], v[210:213], v[40:43]
	v_mfma_f32_16x16x32_bf16 v[72:75], v[136:139], v[210:213], v[72:75]
	v_mfma_f32_16x16x32_bf16 v[104:107], v[140:143], v[210:213], v[104:107]
	v_mfma_f32_16x16x32_bf16 v[12:15], v[128:131], v[214:217], v[12:15]
	v_mfma_f32_16x16x32_bf16 v[44:47], v[132:135], v[214:217], v[44:47]
	v_mfma_f32_16x16x32_bf16 v[76:79], v[136:139], v[214:217], v[76:79]
	v_mfma_f32_16x16x32_bf16 v[108:111], v[140:143], v[214:217], v[108:111]
	ds_read_b128 v[198:201], v245 offset:0
	ds_read_b128 v[202:205], v245 offset:2048
	ds_read_b128 v[210:213], v245 offset:4096
	ds_read_b128 v[214:217], v245 offset:6144
	s_waitcnt lgkmcnt(4)
	v_mfma_f32_16x16x32_bf16 v[16:19], v[128:131], v[218:221], v[16:19]
	v_mfma_f32_16x16x32_bf16 v[48:51], v[132:135], v[218:221], v[48:51]
	v_mfma_f32_16x16x32_bf16 v[80:83], v[136:139], v[218:221], v[80:83]
	v_mfma_f32_16x16x32_bf16 v[112:115], v[140:143], v[218:221], v[112:115]
	v_mfma_f32_16x16x32_bf16 v[20:23], v[128:131], v[222:225], v[20:23]
	v_mfma_f32_16x16x32_bf16 v[52:55], v[132:135], v[222:225], v[52:55]
	v_mfma_f32_16x16x32_bf16 v[84:87], v[136:139], v[222:225], v[84:87]
	v_mfma_f32_16x16x32_bf16 v[116:119], v[140:143], v[222:225], v[116:119]
	v_mfma_f32_16x16x32_bf16 v[24:27], v[128:131], v[226:229], v[24:27]
	v_mfma_f32_16x16x32_bf16 v[56:59], v[132:135], v[226:229], v[56:59]
	v_mfma_f32_16x16x32_bf16 v[88:91], v[136:139], v[226:229], v[88:91]
	v_mfma_f32_16x16x32_bf16 v[120:123], v[140:143], v[226:229], v[120:123]
	v_mfma_f32_16x16x32_bf16 v[28:31], v[128:131], v[230:233], v[28:31]
	v_mfma_f32_16x16x32_bf16 v[60:63], v[132:135], v[230:233], v[60:63]
	v_mfma_f32_16x16x32_bf16 v[92:95], v[136:139], v[230:233], v[92:95]
	v_mfma_f32_16x16x32_bf16 v[124:127], v[140:143], v[230:233], v[124:127]
	ds_read_b128 v[218:221], v245 offset:8192
	ds_read_b128 v[222:225], v245 offset:10240
	ds_read_b128 v[226:229], v245 offset:12288
	ds_read_b128 v[230:233], v245 offset:14336
	s_waitcnt vmcnt(16)
	global_load_dwordx4 v[128:131], v238, s[56:57]
	global_load_dwordx4 v[132:135], v239, s[56:57]
	global_load_dwordx4 v[136:139], v240, s[56:57]
	global_load_dwordx4 v[140:143], v241, s[56:57]
	s_cmp_eq_u32 s25, 31
	s_cbranch_scc1 .Lg1_sww2
	s_add_u32 s56, s56, 1024
	s_addc_u32 s57, s57, 0
	s_branch .Lg1_swdw2

.Lg1_ndw2:
.Lg1_swdw2:
	s_add_i32 s25, s25, 1
	s_waitcnt lgkmcnt(4)
	v_mfma_f32_16x16x32_bf16 v[0:3], v[144:147], v[198:201], v[0:3]
	v_mfma_f32_16x16x32_bf16 v[32:35], v[148:151], v[198:201], v[32:35]
	v_mfma_f32_16x16x32_bf16 v[64:67], v[152:155], v[198:201], v[64:67]
	v_mfma_f32_16x16x32_bf16 v[96:99], v[156:159], v[198:201], v[96:99]
	v_mfma_f32_16x16x32_bf16 v[4:7], v[144:147], v[202:205], v[4:7]
	v_mfma_f32_16x16x32_bf16 v[36:39], v[148:151], v[202:205], v[36:39]
	v_mfma_f32_16x16x32_bf16 v[68:71], v[152:155], v[202:205], v[68:71]
	v_mfma_f32_16x16x32_bf16 v[100:103], v[156:159], v[202:205], v[100:103]
	v_mfma_f32_16x16x32_bf16 v[8:11], v[144:147], v[210:213], v[8:11]
	v_mfma_f32_16x16x32_bf16 v[40:43], v[148:151], v[210:213], v[40:43]
	v_mfma_f32_16x16x32_bf16 v[72:75], v[152:155], v[210:213], v[72:75]
	v_mfma_f32_16x16x32_bf16 v[104:107], v[156:159], v[210:213], v[104:107]
	v_mfma_f32_16x16x32_bf16 v[12:15], v[144:147], v[214:217], v[12:15]
	v_mfma_f32_16x16x32_bf16 v[44:47], v[148:151], v[214:217], v[44:47]
	v_mfma_f32_16x16x32_bf16 v[76:79], v[152:155], v[214:217], v[76:79]
	v_mfma_f32_16x16x32_bf16 v[108:111], v[156:159], v[214:217], v[108:111]
	s_waitcnt lgkmcnt(0)
	v_mfma_f32_16x16x32_bf16 v[16:19], v[144:147], v[218:221], v[16:19]
	v_mfma_f32_16x16x32_bf16 v[48:51], v[148:151], v[218:221], v[48:51]
	v_mfma_f32_16x16x32_bf16 v[80:83], v[152:155], v[218:221], v[80:83]
	v_mfma_f32_16x16x32_bf16 v[112:115], v[156:159], v[218:221], v[112:115]
	v_mfma_f32_16x16x32_bf16 v[20:23], v[144:147], v[222:225], v[20:23]
	v_mfma_f32_16x16x32_bf16 v[52:55], v[148:151], v[222:225], v[52:55]
	v_mfma_f32_16x16x32_bf16 v[84:87], v[152:155], v[222:225], v[84:87]
	v_mfma_f32_16x16x32_bf16 v[116:119], v[156:159], v[222:225], v[116:119]
	v_mfma_f32_16x16x32_bf16 v[24:27], v[144:147], v[226:229], v[24:27]
	v_mfma_f32_16x16x32_bf16 v[56:59], v[148:151], v[226:229], v[56:59]
	v_mfma_f32_16x16x32_bf16 v[88:91], v[152:155], v[226:229], v[88:91]
	v_mfma_f32_16x16x32_bf16 v[120:123], v[156:159], v[226:229], v[120:123]
	v_mfma_f32_16x16x32_bf16 v[28:31], v[144:147], v[230:233], v[28:31]
	v_mfma_f32_16x16x32_bf16 v[60:63], v[148:151], v[230:233], v[60:63]
	v_mfma_f32_16x16x32_bf16 v[92:95], v[152:155], v[230:233], v[92:95]
	v_mfma_f32_16x16x32_bf16 v[124:127], v[156:159], v[230:233], v[124:127]
	s_add_i32 s28, s28, 0x4000
	s_cmp_lt_u32 s28, 0xc000
	s_cselect_b32 s28, s28, 0
	s_add_i32 s27, s27, 0x4000
	s_cmp_lt_u32 s27, 0xc000
	s_cselect_b32 s27, s27, 0
	s_add_i32 s29, s29, 1
	s_waitcnt vmcnt(12)
	s_barrier
	v_add_u32_e32 v244, s28, v242
	v_add_u32_e32 v245, s28, v243
	ds_read_b128 v[198:201], v244 offset:0
	ds_read_b128 v[202:205], v244 offset:2048
	ds_read_b128 v[210:213], v244 offset:4096
	ds_read_b128 v[214:217], v244 offset:6144
	ds_read_b128 v[218:221], v244 offset:8192
	ds_read_b128 v[222:225], v244 offset:10240
	ds_read_b128 v[226:229], v244 offset:12288
	ds_read_b128 v[230:233], v244 offset:14336
	global_load_dwordx4 v[144:147], v238, s[56:57]
	global_load_dwordx4 v[148:151], v239, s[56:57]
	global_load_dwordx4 v[152:155], v240, s[56:57]
	global_load_dwordx4 v[156:159], v241, s[56:57]
	s_cmp_eq_u32 s25, 31
	s_cbranch_scc1 .Lg1_sww3
	s_add_u32 s56, s56, 1024
	s_addc_u32 s57, s57, 0
	s_branch .Lg1_swdw3

.Lg1_nda4:
.Lg1_sada4:
	s_waitcnt lgkmcnt(4)
	v_mfma_f32_16x16x32_bf16 v[0:3], v[160:163], v[198:201], v[0:3]
	v_mfma_f32_16x16x32_bf16 v[32:35], v[164:167], v[198:201], v[32:35]
	v_mfma_f32_16x16x32_bf16 v[64:67], v[168:171], v[198:201], v[64:67]
	v_mfma_f32_16x16x32_bf16 v[96:99], v[172:175], v[198:201], v[96:99]
	v_mfma_f32_16x16x32_bf16 v[4:7], v[160:163], v[202:205], v[4:7]
	v_mfma_f32_16x16x32_bf16 v[36:39], v[164:167], v[202:205], v[36:39]
	v_mfma_f32_16x16x32_bf16 v[68:71], v[168:171], v[202:205], v[68:71]
	v_mfma_f32_16x16x32_bf16 v[100:103], v[172:175], v[202:205], v[100:103]
	v_mfma_f32_16x16x32_bf16 v[8:11], v[160:163], v[210:213], v[8:11]
	v_mfma_f32_16x16x32_bf16 v[40:43], v[164:167], v[210:213], v[40:43]
	v_mfma_f32_16x16x32_bf16 v[72:75], v[168:171], v[210:213], v[72:75]
	v_mfma_f32_16x16x32_bf16 v[104:107], v[172:175], v[210:213], v[104:107]
	v_mfma_f32_16x16x32_bf16 v[12:15], v[160:163], v[214:217], v[12:15]
	v_mfma_f32_16x16x32_bf16 v[44:47], v[164:167], v[214:217], v[44:47]
	v_mfma_f32_16x16x32_bf16 v[76:79], v[168:171], v[214:217], v[76:79]
	v_mfma_f32_16x16x32_bf16 v[108:111], v[172:175], v[214:217], v[108:111]
	ds_read_b128 v[198:201], v245 offset:0
	ds_read_b128 v[202:205], v245 offset:2048
	ds_read_b128 v[210:213], v245 offset:4096
	ds_read_b128 v[214:217], v245 offset:6144
	s_waitcnt lgkmcnt(4)
	v_mfma_f32_16x16x32_bf16 v[16:19], v[160:163], v[218:221], v[16:19]
	v_mfma_f32_16x16x32_bf16 v[48:51], v[164:167], v[218:221], v[48:51]
	v_mfma_f32_16x16x32_bf16 v[80:83], v[168:171], v[218:221], v[80:83]
	v_mfma_f32_16x16x32_bf16 v[112:115], v[172:175], v[218:221], v[112:115]
	v_mfma_f32_16x16x32_bf16 v[20:23], v[160:163], v[222:225], v[20:23]
	v_mfma_f32_16x16x32_bf16 v[52:55], v[164:167], v[222:225], v[52:55]
	v_mfma_f32_16x16x32_bf16 v[84:87], v[168:171], v[222:225], v[84:87]
	v_mfma_f32_16x16x32_bf16 v[116:119], v[172:175], v[222:225], v[116:119]
	v_mfma_f32_16x16x32_bf16 v[24:27], v[160:163], v[226:229], v[24:27]
	v_mfma_f32_16x16x32_bf16 v[56:59], v[164:167], v[226:229], v[56:59]
	v_mfma_f32_16x16x32_bf16 v[88:91], v[168:171], v[226:229], v[88:91]
	v_mfma_f32_16x16x32_bf16 v[120:123], v[172:175], v[226:229], v[120:123]
	v_mfma_f32_16x16x32_bf16 v[28:31], v[160:163], v[230:233], v[28:31]
	v_mfma_f32_16x16x32_bf16 v[60:63], v[164:167], v[230:233], v[60:63]
	v_mfma_f32_16x16x32_bf16 v[92:95], v[168:171], v[230:233], v[92:95]
	v_mfma_f32_16x16x32_bf16 v[124:127], v[172:175], v[230:233], v[124:127]
	ds_read_b128 v[218:221], v245 offset:8192
	ds_read_b128 v[222:225], v245 offset:10240
	ds_read_b128 v[226:229], v245 offset:12288
	ds_read_b128 v[230:233], v245 offset:14336
	s_waitcnt vmcnt(16)
	global_load_dwordx4 v[160:163], v238, s[56:57]
	global_load_dwordx4 v[164:167], v239, s[56:57]
	global_load_dwordx4 v[168:171], v240, s[56:57]
	global_load_dwordx4 v[172:175], v241, s[56:57]
	s_cmp_eq_u32 s25, 31
	s_cbranch_scc1 .Lg1_sww5
	s_add_u32 s56, s56, 1024
	s_addc_u32 s57, s57, 0
	s_branch .Lg1_swdw5

.Lg2_loop:
	s_waitcnt vmcnt(12)
	s_barrier
	v_add_u32_e32 v244, s56, v242
	v_add_u32_e32 v245, s56, v243
	ds_read_b128 v[200:203], v244 offset:0
	ds_read_b128 v[204:207], v244 offset:2048
	ds_read_b128 v[210:213], v244 offset:4096
	ds_read_b128 v[214:217], v244 offset:6144
	ds_read_b128 v[218:221], v244 offset:8192
	ds_read_b128 v[222:225], v244 offset:10240
	ds_read_b128 v[226:229], v244 offset:12288
	ds_read_b128 v[230:233], v244 offset:14336
	global_load_dwordx4 v[176:179], v238, s[54:55]
	global_load_dwordx4 v[184:187], v239, s[54:55]
	global_load_dwordx4 v[188:191], v240, s[54:55]
	global_load_dwordx4 v[196:199], v241, s[54:55]
	s_cmp_eq_u32 s59, 31
	s_cbranch_scc1 .Lg2_sww0
	s_add_u32 s54, s54, 1024
	s_addc_u32 s55, s55, 0
	s_branch .Lg2_swdw0

.Lg2_nda1:
.Lg2_sada1:
	s_waitcnt lgkmcnt(4)
	v_mfma_f32_16x16x32_bf16 v[0:3], v[128:131], v[200:203], v[0:3]
	v_mfma_f32_16x16x32_bf16 v[32:35], v[132:135], v[200:203], v[32:35]
	v_mfma_f32_16x16x32_bf16 v[64:67], v[136:139], v[200:203], v[64:67]
	v_mfma_f32_16x16x32_bf16 v[96:99], v[140:143], v[200:203], v[96:99]
	v_mfma_f32_16x16x32_bf16 v[4:7], v[128:131], v[204:207], v[4:7]
	v_mfma_f32_16x16x32_bf16 v[36:39], v[132:135], v[204:207], v[36:39]
	v_mfma_f32_16x16x32_bf16 v[68:71], v[136:139], v[204:207], v[68:71]
	v_mfma_f32_16x16x32_bf16 v[100:103], v[140:143], v[204:207], v[100:103]
	v_mfma_f32_16x16x32_bf16 v[8:11], v[128:131], v[210:213], v[8:11]
	v_mfma_f32_16x16x32_bf16 v[40:43], v[132:135], v[210:213], v[40:43]
	v_mfma_f32_16x16x32_bf16 v[72:75], v[136:139], v[210:213], v[72:75]
	v_mfma_f32_16x16x32_bf16 v[104:107], v[140:143], v[210:213], v[104:107]
	v_mfma_f32_16x16x32_bf16 v[12:15], v[128:131], v[214:217], v[12:15]
	v_mfma_f32_16x16x32_bf16 v[44:47], v[132:135], v[214:217], v[44:47]
	v_mfma_f32_16x16x32_bf16 v[76:79], v[136:139], v[214:217], v[76:79]
	v_mfma_f32_16x16x32_bf16 v[108:111], v[140:143], v[214:217], v[108:111]
	ds_read_b128 v[200:203], v245 offset:0
	ds_read_b128 v[204:207], v245 offset:2048
	ds_read_b128 v[210:213], v245 offset:4096
	ds_read_b128 v[214:217], v245 offset:6144
	s_waitcnt lgkmcnt(4)
	v_mfma_f32_16x16x32_bf16 v[16:19], v[128:131], v[218:221], v[16:19]
	v_mfma_f32_16x16x32_bf16 v[48:51], v[132:135], v[218:221], v[48:51]
	v_mfma_f32_16x16x32_bf16 v[80:83], v[136:139], v[218:221], v[80:83]
	v_mfma_f32_16x16x32_bf16 v[112:115], v[140:143], v[218:221], v[112:115]
	v_mfma_f32_16x16x32_bf16 v[20:23], v[128:131], v[222:225], v[20:23]
	v_mfma_f32_16x16x32_bf16 v[52:55], v[132:135], v[222:225], v[52:55]
	v_mfma_f32_16x16x32_bf16 v[84:87], v[136:139], v[222:225], v[84:87]
	v_mfma_f32_16x16x32_bf16 v[116:119], v[140:143], v[222:225], v[116:119]
	v_mfma_f32_16x16x32_bf16 v[24:27], v[128:131], v[226:229], v[24:27]
	v_mfma_f32_16x16x32_bf16 v[56:59], v[132:135], v[226:229], v[56:59]
	v_mfma_f32_16x16x32_bf16 v[88:91], v[136:139], v[226:229], v[88:91]
	v_mfma_f32_16x16x32_bf16 v[120:123], v[140:143], v[226:229], v[120:123]
	v_mfma_f32_16x16x32_bf16 v[28:31], v[128:131], v[230:233], v[28:31]
	v_mfma_f32_16x16x32_bf16 v[60:63], v[132:135], v[230:233], v[60:63]
	v_mfma_f32_16x16x32_bf16 v[92:95], v[136:139], v[230:233], v[92:95]
	v_mfma_f32_16x16x32_bf16 v[124:127], v[140:143], v[230:233], v[124:127]
	ds_read_b128 v[218:221], v245 offset:8192
	ds_read_b128 v[222:225], v245 offset:10240
	ds_read_b128 v[226:229], v245 offset:12288
	ds_read_b128 v[230:233], v245 offset:14336
	s_waitcnt vmcnt(16)
	global_load_dwordx4 v[128:131], v238, s[54:55]
	global_load_dwordx4 v[132:135], v239, s[54:55]
	global_load_dwordx4 v[136:139], v240, s[54:55]
	global_load_dwordx4 v[140:143], v241, s[54:55]
	s_cmp_eq_u32 s59, 31
	s_cbranch_scc1 .Lg2_sww2
	s_add_u32 s54, s54, 1024
	s_addc_u32 s55, s55, 0
	s_branch .Lg2_swdw2

.Lg2_wndw2:
.Lg2_swdw2:
	s_add_i32 s59, s59, 1
	s_waitcnt lgkmcnt(4)
	v_mfma_f32_16x16x32_bf16 v[0:3], v[144:147], v[200:203], v[0:3]
	v_mfma_f32_16x16x32_bf16 v[32:35], v[148:151], v[200:203], v[32:35]
	v_mfma_f32_16x16x32_bf16 v[64:67], v[152:155], v[200:203], v[64:67]
	v_mfma_f32_16x16x32_bf16 v[96:99], v[156:159], v[200:203], v[96:99]
	v_mfma_f32_16x16x32_bf16 v[4:7], v[144:147], v[204:207], v[4:7]
	v_mfma_f32_16x16x32_bf16 v[36:39], v[148:151], v[204:207], v[36:39]
	v_mfma_f32_16x16x32_bf16 v[68:71], v[152:155], v[204:207], v[68:71]
	v_mfma_f32_16x16x32_bf16 v[100:103], v[156:159], v[204:207], v[100:103]
	v_mfma_f32_16x16x32_bf16 v[8:11], v[144:147], v[210:213], v[8:11]
	v_mfma_f32_16x16x32_bf16 v[40:43], v[148:151], v[210:213], v[40:43]
	v_mfma_f32_16x16x32_bf16 v[72:75], v[152:155], v[210:213], v[72:75]
	v_mfma_f32_16x16x32_bf16 v[104:107], v[156:159], v[210:213], v[104:107]
	v_mfma_f32_16x16x32_bf16 v[12:15], v[144:147], v[214:217], v[12:15]
	v_mfma_f32_16x16x32_bf16 v[44:47], v[148:151], v[214:217], v[44:47]
	v_mfma_f32_16x16x32_bf16 v[76:79], v[152:155], v[214:217], v[76:79]
	v_mfma_f32_16x16x32_bf16 v[108:111], v[156:159], v[214:217], v[108:111]
	s_waitcnt lgkmcnt(0)
	v_mfma_f32_16x16x32_bf16 v[16:19], v[144:147], v[218:221], v[16:19]
	v_mfma_f32_16x16x32_bf16 v[48:51], v[148:151], v[218:221], v[48:51]
	v_mfma_f32_16x16x32_bf16 v[80:83], v[152:155], v[218:221], v[80:83]
	v_mfma_f32_16x16x32_bf16 v[112:115], v[156:159], v[218:221], v[112:115]
	v_mfma_f32_16x16x32_bf16 v[20:23], v[144:147], v[222:225], v[20:23]
	v_mfma_f32_16x16x32_bf16 v[52:55], v[148:151], v[222:225], v[52:55]
	v_mfma_f32_16x16x32_bf16 v[84:87], v[152:155], v[222:225], v[84:87]
	v_mfma_f32_16x16x32_bf16 v[116:119], v[156:159], v[222:225], v[116:119]
	v_mfma_f32_16x16x32_bf16 v[24:27], v[144:147], v[226:229], v[24:27]
	v_mfma_f32_16x16x32_bf16 v[56:59], v[148:151], v[226:229], v[56:59]
	v_mfma_f32_16x16x32_bf16 v[88:91], v[152:155], v[226:229], v[88:91]
	v_mfma_f32_16x16x32_bf16 v[120:123], v[156:159], v[226:229], v[120:123]
	v_mfma_f32_16x16x32_bf16 v[28:31], v[144:147], v[230:233], v[28:31]
	v_mfma_f32_16x16x32_bf16 v[60:63], v[148:151], v[230:233], v[60:63]
	v_mfma_f32_16x16x32_bf16 v[92:95], v[152:155], v[230:233], v[92:95]
	v_mfma_f32_16x16x32_bf16 v[124:127], v[156:159], v[230:233], v[124:127]
	s_add_i32 s56, s56, 0x4000
	s_cmp_lt_u32 s56, 0xc000
	s_cselect_b32 s56, s56, 0
	s_add_i32 s57, s57, 0x4000
	s_cmp_lt_u32 s57, 0xc000
	s_cselect_b32 s57, s57, 0
	s_add_i32 s58, s58, 1
	s_waitcnt vmcnt(12)
	s_barrier
	v_add_u32_e32 v244, s56, v242
	v_add_u32_e32 v245, s56, v243
	ds_read_b128 v[200:203], v244 offset:0
	ds_read_b128 v[204:207], v244 offset:2048
	ds_read_b128 v[210:213], v244 offset:4096
	ds_read_b128 v[214:217], v244 offset:6144
	ds_read_b128 v[218:221], v244 offset:8192
	ds_read_b128 v[222:225], v244 offset:10240
	ds_read_b128 v[226:229], v244 offset:12288
	ds_read_b128 v[230:233], v244 offset:14336
	global_load_dwordx4 v[144:147], v238, s[54:55]
	global_load_dwordx4 v[148:151], v239, s[54:55]
	global_load_dwordx4 v[152:155], v240, s[54:55]
	global_load_dwordx4 v[156:159], v241, s[54:55]
	s_cmp_eq_u32 s59, 31
	s_cbranch_scc1 .Lg2_sww3
	s_add_u32 s54, s54, 1024
	s_addc_u32 s55, s55, 0
	s_branch .Lg2_swdw3

.Lg2_nda4:
.Lg2_sada4:
	s_waitcnt lgkmcnt(4)
	v_mfma_f32_16x16x32_bf16 v[0:3], v[160:163], v[200:203], v[0:3]
	v_mfma_f32_16x16x32_bf16 v[32:35], v[164:167], v[200:203], v[32:35]
	v_mfma_f32_16x16x32_bf16 v[64:67], v[168:171], v[200:203], v[64:67]
	v_mfma_f32_16x16x32_bf16 v[96:99], v[172:175], v[200:203], v[96:99]
	v_mfma_f32_16x16x32_bf16 v[4:7], v[160:163], v[204:207], v[4:7]
	v_mfma_f32_16x16x32_bf16 v[36:39], v[164:167], v[204:207], v[36:39]
	v_mfma_f32_16x16x32_bf16 v[68:71], v[168:171], v[204:207], v[68:71]
	v_mfma_f32_16x16x32_bf16 v[100:103], v[172:175], v[204:207], v[100:103]
	v_mfma_f32_16x16x32_bf16 v[8:11], v[160:163], v[210:213], v[8:11]
	v_mfma_f32_16x16x32_bf16 v[40:43], v[164:167], v[210:213], v[40:43]
	v_mfma_f32_16x16x32_bf16 v[72:75], v[168:171], v[210:213], v[72:75]
	v_mfma_f32_16x16x32_bf16 v[104:107], v[172:175], v[210:213], v[104:107]
	v_mfma_f32_16x16x32_bf16 v[12:15], v[160:163], v[214:217], v[12:15]
	v_mfma_f32_16x16x32_bf16 v[44:47], v[164:167], v[214:217], v[44:47]
	v_mfma_f32_16x16x32_bf16 v[76:79], v[168:171], v[214:217], v[76:79]
	v_mfma_f32_16x16x32_bf16 v[108:111], v[172:175], v[214:217], v[108:111]
	ds_read_b128 v[200:203], v245 offset:0
	ds_read_b128 v[204:207], v245 offset:2048
	ds_read_b128 v[210:213], v245 offset:4096
	ds_read_b128 v[214:217], v245 offset:6144
	s_waitcnt lgkmcnt(4)
	v_mfma_f32_16x16x32_bf16 v[16:19], v[160:163], v[218:221], v[16:19]
	v_mfma_f32_16x16x32_bf16 v[48:51], v[164:167], v[218:221], v[48:51]
	v_mfma_f32_16x16x32_bf16 v[80:83], v[168:171], v[218:221], v[80:83]
	v_mfma_f32_16x16x32_bf16 v[112:115], v[172:175], v[218:221], v[112:115]
	v_mfma_f32_16x16x32_bf16 v[20:23], v[160:163], v[222:225], v[20:23]
	v_mfma_f32_16x16x32_bf16 v[52:55], v[164:167], v[222:225], v[52:55]
	v_mfma_f32_16x16x32_bf16 v[84:87], v[168:171], v[222:225], v[84:87]
	v_mfma_f32_16x16x32_bf16 v[116:119], v[172:175], v[222:225], v[116:119]
	v_mfma_f32_16x16x32_bf16 v[24:27], v[160:163], v[226:229], v[24:27]
	v_mfma_f32_16x16x32_bf16 v[56:59], v[164:167], v[226:229], v[56:59]
	v_mfma_f32_16x16x32_bf16 v[88:91], v[168:171], v[226:229], v[88:91]
	v_mfma_f32_16x16x32_bf16 v[120:123], v[172:175], v[226:229], v[120:123]
	v_mfma_f32_16x16x32_bf16 v[28:31], v[160:163], v[230:233], v[28:31]
	v_mfma_f32_16x16x32_bf16 v[60:63], v[164:167], v[230:233], v[60:63]
	v_mfma_f32_16x16x32_bf16 v[92:95], v[168:171], v[230:233], v[92:95]
	v_mfma_f32_16x16x32_bf16 v[124:127], v[172:175], v[230:233], v[124:127]
	ds_read_b128 v[218:221], v245 offset:8192
	ds_read_b128 v[222:225], v245 offset:10240
	ds_read_b128 v[226:229], v245 offset:12288
	ds_read_b128 v[230:233], v245 offset:14336
	s_waitcnt vmcnt(16)
	global_load_dwordx4 v[160:163], v238, s[54:55]
	global_load_dwordx4 v[164:167], v239, s[54:55]
	global_load_dwordx4 v[168:171], v240, s[54:55]
	global_load_dwordx4 v[172:175], v241, s[54:55]
	s_cmp_eq_u32 s59, 31
	s_cbranch_scc1 .Lg2_sww5
	s_add_u32 s54, s54, 1024
	s_addc_u32 s55, s55, 0
	s_branch .Lg2_swdw5

.Lg3_loop:
	s_waitcnt vmcnt(12)
	s_barrier
	v_add_u32_e32 v244, s16, v242
	v_add_u32_e32 v245, s16, v243
	ds_read_b128 v[198:201], v244 offset:0
	ds_read_b128 v[202:205], v244 offset:2048
	ds_read_b128 v[210:213], v244 offset:4096
	ds_read_b128 v[214:217], v244 offset:6144
	ds_read_b128 v[218:221], v244 offset:8192
	ds_read_b128 v[222:225], v244 offset:10240
	ds_read_b128 v[226:229], v244 offset:12288
	ds_read_b128 v[230:233], v244 offset:14336
	global_load_dwordx4 v[176:179], v238, s[14:15]
	global_load_dwordx4 v[182:185], v239, s[14:15]
	global_load_dwordx4 v[186:189], v240, s[14:15]
	global_load_dwordx4 v[194:197], v241, s[14:15]
	s_cmp_eq_u32 s19, 31
	s_cbranch_scc1 .Lg3_sww0
	s_add_u32 s14, s14, 1024
	s_addc_u32 s15, s15, 0
	s_branch .Lg3_swdw0

.Lg3_nda1:
.Lg3_sada1:
	s_waitcnt lgkmcnt(4)
	v_mfma_f32_16x16x32_bf16 v[0:3], v[128:131], v[198:201], v[0:3]
	v_mfma_f32_16x16x32_bf16 v[32:35], v[132:135], v[198:201], v[32:35]
	v_mfma_f32_16x16x32_bf16 v[64:67], v[136:139], v[198:201], v[64:67]
	v_mfma_f32_16x16x32_bf16 v[96:99], v[140:143], v[198:201], v[96:99]
	v_mfma_f32_16x16x32_bf16 v[4:7], v[128:131], v[202:205], v[4:7]
	v_mfma_f32_16x16x32_bf16 v[36:39], v[132:135], v[202:205], v[36:39]
	v_mfma_f32_16x16x32_bf16 v[68:71], v[136:139], v[202:205], v[68:71]
	v_mfma_f32_16x16x32_bf16 v[100:103], v[140:143], v[202:205], v[100:103]
	v_mfma_f32_16x16x32_bf16 v[8:11], v[128:131], v[210:213], v[8:11]
	v_mfma_f32_16x16x32_bf16 v[40:43], v[132:135], v[210:213], v[40:43]
	v_mfma_f32_16x16x32_bf16 v[72:75], v[136:139], v[210:213], v[72:75]
	v_mfma_f32_16x16x32_bf16 v[104:107], v[140:143], v[210:213], v[104:107]
	v_mfma_f32_16x16x32_bf16 v[12:15], v[128:131], v[214:217], v[12:15]
	v_mfma_f32_16x16x32_bf16 v[44:47], v[132:135], v[214:217], v[44:47]
	v_mfma_f32_16x16x32_bf16 v[76:79], v[136:139], v[214:217], v[76:79]
	v_mfma_f32_16x16x32_bf16 v[108:111], v[140:143], v[214:217], v[108:111]
	ds_read_b128 v[198:201], v245 offset:0
	ds_read_b128 v[202:205], v245 offset:2048
	ds_read_b128 v[210:213], v245 offset:4096
	ds_read_b128 v[214:217], v245 offset:6144
	s_waitcnt lgkmcnt(4)
	v_mfma_f32_16x16x32_bf16 v[16:19], v[128:131], v[218:221], v[16:19]
	v_mfma_f32_16x16x32_bf16 v[48:51], v[132:135], v[218:221], v[48:51]
	v_mfma_f32_16x16x32_bf16 v[80:83], v[136:139], v[218:221], v[80:83]
	v_mfma_f32_16x16x32_bf16 v[112:115], v[140:143], v[218:221], v[112:115]
	v_mfma_f32_16x16x32_bf16 v[20:23], v[128:131], v[222:225], v[20:23]
	v_mfma_f32_16x16x32_bf16 v[52:55], v[132:135], v[222:225], v[52:55]
	v_mfma_f32_16x16x32_bf16 v[84:87], v[136:139], v[222:225], v[84:87]
	v_mfma_f32_16x16x32_bf16 v[116:119], v[140:143], v[222:225], v[116:119]
	v_mfma_f32_16x16x32_bf16 v[24:27], v[128:131], v[226:229], v[24:27]
	v_mfma_f32_16x16x32_bf16 v[56:59], v[132:135], v[226:229], v[56:59]
	v_mfma_f32_16x16x32_bf16 v[88:91], v[136:139], v[226:229], v[88:91]
	v_mfma_f32_16x16x32_bf16 v[120:123], v[140:143], v[226:229], v[120:123]
	v_mfma_f32_16x16x32_bf16 v[28:31], v[128:131], v[230:233], v[28:31]
	v_mfma_f32_16x16x32_bf16 v[60:63], v[132:135], v[230:233], v[60:63]
	v_mfma_f32_16x16x32_bf16 v[92:95], v[136:139], v[230:233], v[92:95]
	v_mfma_f32_16x16x32_bf16 v[124:127], v[140:143], v[230:233], v[124:127]
	ds_read_b128 v[218:221], v245 offset:8192
	ds_read_b128 v[222:225], v245 offset:10240
	ds_read_b128 v[226:229], v245 offset:12288
	ds_read_b128 v[230:233], v245 offset:14336
	s_waitcnt vmcnt(16)
	global_load_dwordx4 v[128:131], v238, s[14:15]
	global_load_dwordx4 v[132:135], v239, s[14:15]
	global_load_dwordx4 v[136:139], v240, s[14:15]
	global_load_dwordx4 v[140:143], v241, s[14:15]
	s_cmp_eq_u32 s19, 31
	s_cbranch_scc1 .Lg3_sww2
	s_add_u32 s14, s14, 1024
	s_addc_u32 s15, s15, 0
	s_branch .Lg3_swdw2

.Lg3_wndw2:
.Lg3_swdw2:
	s_add_i32 s19, s19, 1
	s_waitcnt lgkmcnt(4)
	v_mfma_f32_16x16x32_bf16 v[0:3], v[144:147], v[198:201], v[0:3]
	v_mfma_f32_16x16x32_bf16 v[32:35], v[148:151], v[198:201], v[32:35]
	v_mfma_f32_16x16x32_bf16 v[64:67], v[152:155], v[198:201], v[64:67]
	v_mfma_f32_16x16x32_bf16 v[96:99], v[156:159], v[198:201], v[96:99]
	v_mfma_f32_16x16x32_bf16 v[4:7], v[144:147], v[202:205], v[4:7]
	v_mfma_f32_16x16x32_bf16 v[36:39], v[148:151], v[202:205], v[36:39]
	v_mfma_f32_16x16x32_bf16 v[68:71], v[152:155], v[202:205], v[68:71]
	v_mfma_f32_16x16x32_bf16 v[100:103], v[156:159], v[202:205], v[100:103]
	v_mfma_f32_16x16x32_bf16 v[8:11], v[144:147], v[210:213], v[8:11]
	v_mfma_f32_16x16x32_bf16 v[40:43], v[148:151], v[210:213], v[40:43]
	v_mfma_f32_16x16x32_bf16 v[72:75], v[152:155], v[210:213], v[72:75]
	v_mfma_f32_16x16x32_bf16 v[104:107], v[156:159], v[210:213], v[104:107]
	v_mfma_f32_16x16x32_bf16 v[12:15], v[144:147], v[214:217], v[12:15]
	v_mfma_f32_16x16x32_bf16 v[44:47], v[148:151], v[214:217], v[44:47]
	v_mfma_f32_16x16x32_bf16 v[76:79], v[152:155], v[214:217], v[76:79]
	v_mfma_f32_16x16x32_bf16 v[108:111], v[156:159], v[214:217], v[108:111]
	s_waitcnt lgkmcnt(0)
	v_mfma_f32_16x16x32_bf16 v[16:19], v[144:147], v[218:221], v[16:19]
	v_mfma_f32_16x16x32_bf16 v[48:51], v[148:151], v[218:221], v[48:51]
	v_mfma_f32_16x16x32_bf16 v[80:83], v[152:155], v[218:221], v[80:83]
	v_mfma_f32_16x16x32_bf16 v[112:115], v[156:159], v[218:221], v[112:115]
	v_mfma_f32_16x16x32_bf16 v[20:23], v[144:147], v[222:225], v[20:23]
	v_mfma_f32_16x16x32_bf16 v[52:55], v[148:151], v[222:225], v[52:55]
	v_mfma_f32_16x16x32_bf16 v[84:87], v[152:155], v[222:225], v[84:87]
	v_mfma_f32_16x16x32_bf16 v[116:119], v[156:159], v[222:225], v[116:119]
	v_mfma_f32_16x16x32_bf16 v[24:27], v[144:147], v[226:229], v[24:27]
	v_mfma_f32_16x16x32_bf16 v[56:59], v[148:151], v[226:229], v[56:59]
	v_mfma_f32_16x16x32_bf16 v[88:91], v[152:155], v[226:229], v[88:91]
	v_mfma_f32_16x16x32_bf16 v[120:123], v[156:159], v[226:229], v[120:123]
	v_mfma_f32_16x16x32_bf16 v[28:31], v[144:147], v[230:233], v[28:31]
	v_mfma_f32_16x16x32_bf16 v[60:63], v[148:151], v[230:233], v[60:63]
	v_mfma_f32_16x16x32_bf16 v[92:95], v[152:155], v[230:233], v[92:95]
	v_mfma_f32_16x16x32_bf16 v[124:127], v[156:159], v[230:233], v[124:127]
	s_add_i32 s16, s16, 0x4000
	s_cmp_lt_u32 s16, 0xc000
	s_cselect_b32 s16, s16, 0
	s_add_i32 s17, s17, 0x4000
	s_cmp_lt_u32 s17, 0xc000
	s_cselect_b32 s17, s17, 0
	s_add_i32 s18, s18, 1
	s_waitcnt vmcnt(12)
	s_barrier
	v_add_u32_e32 v244, s16, v242
	v_add_u32_e32 v245, s16, v243
	ds_read_b128 v[198:201], v244 offset:0
	ds_read_b128 v[202:205], v244 offset:2048
	ds_read_b128 v[210:213], v244 offset:4096
	ds_read_b128 v[214:217], v244 offset:6144
	ds_read_b128 v[218:221], v244 offset:8192
	ds_read_b128 v[222:225], v244 offset:10240
	ds_read_b128 v[226:229], v244 offset:12288
	ds_read_b128 v[230:233], v244 offset:14336
	global_load_dwordx4 v[144:147], v238, s[14:15]
	global_load_dwordx4 v[148:151], v239, s[14:15]
	global_load_dwordx4 v[152:155], v240, s[14:15]
	global_load_dwordx4 v[156:159], v241, s[14:15]
	s_cmp_eq_u32 s19, 31
	s_cbranch_scc1 .Lg3_sww3
	s_add_u32 s14, s14, 1024
	s_addc_u32 s15, s15, 0
	s_branch .Lg3_swdw3

.Lg3_nda4:
.Lg3_sada4:
	s_waitcnt lgkmcnt(4)
	v_mfma_f32_16x16x32_bf16 v[0:3], v[160:163], v[198:201], v[0:3]
	v_mfma_f32_16x16x32_bf16 v[32:35], v[164:167], v[198:201], v[32:35]
	v_mfma_f32_16x16x32_bf16 v[64:67], v[168:171], v[198:201], v[64:67]
	v_mfma_f32_16x16x32_bf16 v[96:99], v[172:175], v[198:201], v[96:99]
	v_mfma_f32_16x16x32_bf16 v[4:7], v[160:163], v[202:205], v[4:7]
	v_mfma_f32_16x16x32_bf16 v[36:39], v[164:167], v[202:205], v[36:39]
	v_mfma_f32_16x16x32_bf16 v[68:71], v[168:171], v[202:205], v[68:71]
	v_mfma_f32_16x16x32_bf16 v[100:103], v[172:175], v[202:205], v[100:103]
	v_mfma_f32_16x16x32_bf16 v[8:11], v[160:163], v[210:213], v[8:11]
	v_mfma_f32_16x16x32_bf16 v[40:43], v[164:167], v[210:213], v[40:43]
	v_mfma_f32_16x16x32_bf16 v[72:75], v[168:171], v[210:213], v[72:75]
	v_mfma_f32_16x16x32_bf16 v[104:107], v[172:175], v[210:213], v[104:107]
	v_mfma_f32_16x16x32_bf16 v[12:15], v[160:163], v[214:217], v[12:15]
	v_mfma_f32_16x16x32_bf16 v[44:47], v[164:167], v[214:217], v[44:47]
	v_mfma_f32_16x16x32_bf16 v[76:79], v[168:171], v[214:217], v[76:79]
	v_mfma_f32_16x16x32_bf16 v[108:111], v[172:175], v[214:217], v[108:111]
	ds_read_b128 v[198:201], v245 offset:0
	ds_read_b128 v[202:205], v245 offset:2048
	ds_read_b128 v[210:213], v245 offset:4096
	ds_read_b128 v[214:217], v245 offset:6144
	s_waitcnt lgkmcnt(4)
	v_mfma_f32_16x16x32_bf16 v[16:19], v[160:163], v[218:221], v[16:19]
	v_mfma_f32_16x16x32_bf16 v[48:51], v[164:167], v[218:221], v[48:51]
	v_mfma_f32_16x16x32_bf16 v[80:83], v[168:171], v[218:221], v[80:83]
	v_mfma_f32_16x16x32_bf16 v[112:115], v[172:175], v[218:221], v[112:115]
	v_mfma_f32_16x16x32_bf16 v[20:23], v[160:163], v[222:225], v[20:23]
	v_mfma_f32_16x16x32_bf16 v[52:55], v[164:167], v[222:225], v[52:55]
	v_mfma_f32_16x16x32_bf16 v[84:87], v[168:171], v[222:225], v[84:87]
	v_mfma_f32_16x16x32_bf16 v[116:119], v[172:175], v[222:225], v[116:119]
	v_mfma_f32_16x16x32_bf16 v[24:27], v[160:163], v[226:229], v[24:27]
	v_mfma_f32_16x16x32_bf16 v[56:59], v[164:167], v[226:229], v[56:59]
	v_mfma_f32_16x16x32_bf16 v[88:91], v[168:171], v[226:229], v[88:91]
	v_mfma_f32_16x16x32_bf16 v[120:123], v[172:175], v[226:229], v[120:123]
	v_mfma_f32_16x16x32_bf16 v[28:31], v[160:163], v[230:233], v[28:31]
	v_mfma_f32_16x16x32_bf16 v[60:63], v[164:167], v[230:233], v[60:63]
	v_mfma_f32_16x16x32_bf16 v[92:95], v[168:171], v[230:233], v[92:95]
	v_mfma_f32_16x16x32_bf16 v[124:127], v[172:175], v[230:233], v[124:127]
	ds_read_b128 v[218:221], v245 offset:8192
	ds_read_b128 v[222:225], v245 offset:10240
	ds_read_b128 v[226:229], v245 offset:12288
	ds_read_b128 v[230:233], v245 offset:14336
	s_waitcnt vmcnt(16)
	global_load_dwordx4 v[160:163], v238, s[14:15]
	global_load_dwordx4 v[164:167], v239, s[14:15]
	global_load_dwordx4 v[168:171], v240, s[14:15]
	global_load_dwordx4 v[172:175], v241, s[14:15]
	s_cmp_eq_u32 s19, 31
	s_cbranch_scc1 .Lg3_sww5
	s_add_u32 s14, s14, 1024
	s_addc_u32 s15, s15, 0
	s_branch .Lg3_swdw5
